# retention waves 4-7: rssq cross-half reduction via v_permlane32_swap instead of ds_bpermute, rssq store global (on v47)
# speedup vs baseline: 1.0143x; 1.0047x over previous
; #define LAS __attribute__((address_space(3)))
; __device__ __forceinline__ unsigned cvt_pk_bf16(float lo, float hi) { f32x2 v = {lo, hi}; bf16x2_t b = __builtin_convertvector(v, bf16x2_t); return __builtin_bit_cast(unsigned, b); }
; __device__ __forceinline__ void ret_mfma(const Params& P, LAS unsigned char* lds, int wave) {
;     ...
;                     for (int i = 0; i < 16; ++i) { const int dv = vb * 32 + 8 * (i >> 2) + 4 * hf + (i & 3);
;                         *(LAS bf16_t*)(lds + ST_OFF + dv * QP + (wave * 32 + q32) * 2) = (bf16_t)(cvt_pk_bf16(st[vb][i], 0.f) & 0xffffu); }
;             }
;             if (wave >= 4) {
;                 const int w4 = wave - 4, dvblk = w4 >> 1, nblk = w4 & 1, n = nblk * 32 + q32;
; #pragma unroll
;                 for (int ks = 0; ks < 4; ++ks) {
;                     const LAS unsigned char* p = lds + V_OFF + (16 * ks + trrow) * VP + dvblk * 64 + trcol;
;                     const bf16x8 a = tr_pair(p, p + 4 * VP);
;                     const bf16x8 bs = *(const LAS bf16x8*)(lds + S_OFF + n * SP + (16 * ks + 8 * hf) * 2);
;                     acc = __builtin_amdgcn_mfma_f32_32x32x16_bf16(a, bs, acc, 0, 0, 0);
;                 }
;                 float sq = 0.f;
; #pragma unroll
;                 for (int i = 0; i < 16; ++i) sq += acc[i] * acc[i];
;                 sq += __shfl_xor(sq, 32);
;                 if (hf == 0) rssq[(r0 + n) * 64 + hh * 16 + slice * 2 + dvblk] = sq;
.LBB0_265:
	s_waitcnt lgkmcnt(0)
	s_barrier
	s_and_b64 vcc, exec, s[8:9]
	v_cvt_pk_bf16_f32 v218, v0, v1
	v_cvt_pk_bf16_f32 v219, v2, v3
	ds_write_b64 v242, v[218:219]
	v_cvt_pk_bf16_f32 v220, v4, v5
	v_cvt_pk_bf16_f32 v221, v6, v7
	ds_write_b64 v242, v[220:221] offset:16
	v_cvt_pk_bf16_f32 v222, v8, v9
	v_cvt_pk_bf16_f32 v223, v10, v11
	ds_write_b64 v242, v[222:223] offset:32
	v_cvt_pk_bf16_f32 v224, v12, v13
	v_cvt_pk_bf16_f32 v225, v14, v15
	ds_write_b64 v242, v[224:225] offset:48
	v_cvt_pk_bf16_f32 v218, v16, v17
	v_cvt_pk_bf16_f32 v219, v18, v19
	ds_write_b64 v242, v[218:219] offset:16896
	v_cvt_pk_bf16_f32 v220, v20, v21
	v_cvt_pk_bf16_f32 v221, v22, v23
	ds_write_b64 v242, v[220:221] offset:16912
	v_cvt_pk_bf16_f32 v222, v24, v25
	v_cvt_pk_bf16_f32 v223, v26, v27
	ds_write_b64 v242, v[222:223] offset:16928
	v_cvt_pk_bf16_f32 v224, v28, v29
	v_cvt_pk_bf16_f32 v225, v30, v31
	ds_write_b64 v242, v[224:225] offset:16944
	s_cbranch_vccnz .LBB0_254
	ds_read_b64_tr_b16 v[190:191], v181
	ds_read_b64_tr_b16 v[192:193], v181 offset:768
	v_add_u32_e32 v103, v151, v149
	ds_read_b128 v[194:197], v103
	ds_read_b64_tr_b16 v[198:199], v181 offset:3072
	ds_read_b64_tr_b16 v[200:201], v181 offset:3840
	ds_read_b128 v[202:205], v103 offset:32
	s_waitcnt lgkmcnt(0)
	v_mfma_f32_32x32x16_bf16 v[32:47], v[190:193], v[194:197], v[32:47]
	s_lshl_b32 s8, s29, 6
	s_or_b32 s8, s18, s8
	v_or_b32_e32 v146, s8, v84
	v_mfma_f32_32x32x16_bf16 v[32:47], v[198:201], v[202:205], v[32:47]
	ds_read_b64_tr_b16 v[190:191], v181 offset:6144
	ds_read_b64_tr_b16 v[192:193], v181 offset:6912
	ds_read_b128 v[194:197], v103 offset:64
	ds_read_b64_tr_b16 v[198:199], v181 offset:9216
	ds_read_b64_tr_b16 v[200:201], v181 offset:9984
	ds_read_b128 v[202:205], v103 offset:96
	s_waitcnt lgkmcnt(0)
	v_mfma_f32_32x32x16_bf16 v[32:47], v[190:193], v[194:197], v[32:47]
	v_mfma_f32_32x32x16_bf16 v[32:47], v[198:201], v[202:205], v[32:47]
	s_nop 11
	v_mul_f32_e32 v103, v33, v33
	v_fmac_f32_e32 v103, v32, v32
	v_fmac_f32_e32 v103, v34, v34
	v_fmac_f32_e32 v103, v35, v35
	v_fmac_f32_e32 v103, v36, v36
	v_fmac_f32_e32 v103, v37, v37
	v_fmac_f32_e32 v103, v38, v38
	v_fmac_f32_e32 v103, v39, v39
	v_fmac_f32_e32 v103, v40, v40
	v_fmac_f32_e32 v103, v41, v41
	v_fmac_f32_e32 v103, v42, v42
	v_fmac_f32_e32 v103, v43, v43
	v_fmac_f32_e32 v103, v44, v44
	v_fmac_f32_e32 v103, v45, v45
	v_fmac_f32_e32 v103, v46, v46
	v_fmac_f32_e32 v103, v47, v47
	v_mov_b32_e32 v107, v103
	s_nop 1
	v_permlane32_swap_b32_e32 v103, v107
	s_and_saveexec_b64 s[8:9], s[6:7]
	s_xor_b64 s[8:9], exec, s[8:9]
	v_mov_b32_e32 v147, s19
	s_andn2_saveexec_b64 s[8:9], s[8:9]
	s_cbranch_execz .LBB0_253
	v_mov_b32_e32 v147, s19
	v_lshlrev_b64 v[190:191], 8, v[146:147]
	s_waitcnt lgkmcnt(0)
	v_add_f32_e32 v103, v103, v107
	v_lshl_add_u64 v[190:191], s[20:21], 0, v[190:191]
	global_store_dword v[190:191], v103, off
	s_branch .LBB0_253
